# attention: loop-top flag SALU moved below the K fragment reads; row-max tree split into two interleaved chains
# speedup vs baseline: 1.0259x; 1.0003x over previous
; #define DMA_K(t, sl) do { const char* b_ = Kb + (size_t)(t) * TSTRIDE; const unsigned d_ = RFL(kdst + (sl) * 16384); glds16(b_ + koff[0], d_); glds16(b_ + koff[1], d_ + 1024); } while (0)
; __device__ __forceinline__ float softmax_rel(f32x16& p0, f32x16& p1, bool first, float& m_reg, float& l_reg, bf16x8& pa0, bf16x8& pa1, bf16x8& pa2, bf16x8& pa3) {
;   float pmax = p0[0];
; #pragma unroll
;   for (int r = 1; r < 16; ++r) pmax = fmaxf(pmax, p0[r]);
; #pragma unroll
;   for (int r = 0; r < 16; ++r) pmax = fmaxf(pmax, p1[r]);
;   { auto rr = __builtin_amdgcn_permlane32_swap(__float_as_uint(pmax), __float_as_uint(pmax), false, false);
;     pmax = fmaxf(__uint_as_float(rr[0]), __uint_as_float(rr[1])); }
; template <int mode> ...
;     ...
;   for (int j = 0; j < NT; ++j) {
;     const bool more = j + 2 < NT;
;     if (more) DMA_K(j + 2, s2);
.LBB0_348:
	s_mov_b32 s11, s24
	s_setprio 2
	v_lshl_add_u32 v212, s11, 14, v199
	v_add_u32_e32 v144, v212, v213
	ds_read_b128 v[194:197], v144 offset:0
	ds_read_b128 v[226:229], v144 offset:0x2000
	v_xor_b32_e32 v144, 32, v213
	v_add_u32_e32 v144, v212, v144
	ds_read_b128 v[230:233], v144 offset:0
	ds_read_b128 v[234:237], v144 offset:0x2000
	v_xor_b32_e32 v144, 64, v213
	v_add_u32_e32 v144, v212, v144
	ds_read_b128 v[238:241], v144 offset:0
	ds_read_b128 v[242:245], v144 offset:0x2000
	v_xor_b32_e32 v144, 0x60, v213
	v_add_u32_e32 v144, v212, v144
	ds_read_b128 v[246:249], v144 offset:0
	ds_read_b128 v[214:217], v144 offset:0x2000
	s_add_i32 s12, s10, 2
	s_cmp_lt_u32 s12, s74
	s_cselect_b64 s[56:57], -1, 0
	s_cmp_ge_u32 s12, s74
	s_cselect_b64 s[90:91], -1, 0
	s_and_b64 vcc, exec, s[90:91]
	v_xor_b32_e32 v128, 0x80000000, v224
	v_mov_b32_e32 v129, v128
	v_mov_b32_e32 v130, v128
	v_mov_b32_e32 v131, v128
	v_mov_b32_e32 v132, v128
	v_mov_b32_e32 v133, v128
	v_mov_b32_e32 v134, v128
	v_mov_b32_e32 v135, v128
	v_mov_b32_e32 v136, v128
	v_mov_b32_e32 v137, v128
	v_mov_b32_e32 v138, v128
	v_mov_b32_e32 v139, v128
	v_mov_b32_e32 v140, v128
	v_mov_b32_e32 v141, v128
	v_mov_b32_e32 v142, v128
	v_mov_b32_e32 v143, v128
	s_waitcnt lgkmcnt(6)
	s_nop 1
	v_mfma_f32_32x32x16_bf16 v[144:159], v[194:197], v[188:191], v[128:143]
	v_mfma_f32_32x32x16_bf16 v[128:143], v[226:229], v[188:191], v[128:143]
	v_xor_b32_e32 v194, 0x80, v213
	v_add_u32_e32 v220, v212, v194
	ds_read_b128 v[194:197], v220 offset:0
	ds_read_b128 v[226:229], v220 offset:0x2000
	s_cbranch_vccnz .Lq0_nodma
	s_add_u32 s24, s38, 0xfffff000
	s_addc_u32 s25, s39, -1
	s_lshl_b32 s12, s9, 14
	s_add_i32 s12, s12, s0
	s_mov_b32 s13, m0
	s_mov_b32 m0, s12
	s_nop 0
	global_load_lds_dwordx4 v192, s[24:25]
	s_addk_i32 s12, 0x400
	s_mov_b32 m0, s12
	s_nop 0
	global_load_lds_dwordx4 v202, s[24:25]
	s_mov_b32 m0, s13
.Lq0_nodma:
	s_waitcnt lgkmcnt(6)
	v_mfma_f32_32x32x16_bf16 v[144:159], v[230:233], v[184:187], v[144:159]
	v_mfma_f32_32x32x16_bf16 v[128:143], v[234:237], v[184:187], v[128:143]
	v_xor_b32_e32 v220, 0xa0, v213
	v_add_u32_e32 v220, v212, v220
	ds_read_b128 v[230:233], v220 offset:0
	ds_read_b128 v[234:237], v220 offset:0x2000
	s_waitcnt lgkmcnt(6)
	v_mfma_f32_32x32x16_bf16 v[144:159], v[238:241], v[180:183], v[144:159]
	v_mfma_f32_32x32x16_bf16 v[128:143], v[242:245], v[180:183], v[128:143]
	v_xor_b32_e32 v220, 0xc0, v213
	v_add_u32_e32 v220, v212, v220
	ds_read_b128 v[238:241], v220 offset:0
	ds_read_b128 v[242:245], v220 offset:0x2000
	s_waitcnt lgkmcnt(6)
	v_mfma_f32_32x32x16_bf16 v[144:159], v[246:249], v[176:179], v[144:159]
	v_mfma_f32_32x32x16_bf16 v[128:143], v[214:217], v[176:179], v[128:143]
	v_xor_b32_e32 v214, 0xe0, v213
	v_add_u32_e32 v212, v212, v214
	ds_read_b128 v[214:217], v212 offset:0
	ds_read_b128 v[246:249], v212 offset:0x2000
	s_waitcnt lgkmcnt(6)
	v_mfma_f32_32x32x16_bf16 v[144:159], v[194:197], v[172:175], v[144:159]
	v_mfma_f32_32x32x16_bf16 v[128:143], v[226:229], v[172:175], v[128:143]
	s_waitcnt lgkmcnt(4)
	v_mfma_f32_32x32x16_bf16 v[144:159], v[230:233], v[168:171], v[144:159]
	v_mfma_f32_32x32x16_bf16 v[128:143], v[234:237], v[168:171], v[128:143]
	s_waitcnt lgkmcnt(2)
	v_mfma_f32_32x32x16_bf16 v[144:159], v[238:241], v[164:167], v[144:159]
	v_mfma_f32_32x32x16_bf16 v[128:143], v[242:245], v[164:167], v[128:143]
	s_waitcnt lgkmcnt(0)
	v_mfma_f32_32x32x16_bf16 v[144:159], v[214:217], v[160:163], v[144:159]
	s_cmp_eq_u32 s10, 0
	s_cselect_b64 s[62:63], -1, 0
	s_cmp_lg_u32 s10, 0
	v_mfma_f32_32x32x16_bf16 v[128:143], v[246:249], v[160:163], v[128:143]
	s_nop 7
	v_max_f32_e32 v194, v145, v145
	v_max_f32_e32 v195, v144, v144
	v_max_f32_e32 v194, v195, v194
	v_max3_f32 v194, v194, v146, v147
	v_max3_f32 v194, v194, v148, v149
	v_max3_f32 v195, v128, v129, v130
	v_max3_f32 v194, v194, v150, v151
	v_max3_f32 v195, v195, v131, v132
	v_max3_f32 v194, v194, v152, v153
	v_max3_f32 v195, v195, v133, v134
	v_max3_f32 v194, v194, v154, v155
	v_max3_f32 v195, v195, v135, v136
	v_max3_f32 v194, v194, v156, v157
	v_max3_f32 v195, v195, v137, v138
	v_max3_f32 v194, v194, v158, v159
	v_max3_f32 v195, v195, v139, v140
	v_max3_f32 v195, v195, v141, v142
	v_max3_f32 v194, v194, v195, v143
	v_mov_b32_e32 v195, v194
	s_nop 1
	v_permlane32_swap_b32_e32 v194, v195
	v_max_f32_e32 v195, v195, v195
	v_max_f32_e32 v194, v194, v194
	v_max_f32_e32 v226, v194, v195
	s_cbranch_scc0 .LBB0_371
	v_cmp_lt_f32_e32 vcc, s30, v226
	s_mov_b64 s[24:25], 0
	s_mov_b64 s[96:97], 0
	s_cbranch_vccnz .LBB0_372
	s_and_b64 vcc, exec, s[24:25]
	s_cbranch_vccnz .LBB0_373

; #define DMA_K(t, sl) do { const char* b_ = Kb + (size_t)(t) * TSTRIDE; const unsigned d_ = RFL(kdst + (sl) * 16384); glds16(b_ + koff[0], d_); glds16(b_ + koff[1], d_ + 1024); } while (0)
; __device__ __forceinline__ float softmax_rel(f32x16& p0, f32x16& p1, bool first, float& m_reg, float& l_reg, bf16x8& pa0, bf16x8& pa1, bf16x8& pa2, bf16x8& pa3) {
;   float pmax = p0[0];
; #pragma unroll
;   for (int r = 1; r < 16; ++r) pmax = fmaxf(pmax, p0[r]);
; #pragma unroll
;   for (int r = 0; r < 16; ++r) pmax = fmaxf(pmax, p1[r]);
;   { auto rr = __builtin_amdgcn_permlane32_swap(__float_as_uint(pmax), __float_as_uint(pmax), false, false);
;     pmax = fmaxf(__uint_as_float(rr[0]), __uint_as_float(rr[1])); }
; template <int mode> ...
;     ...
;   for (int j = 0; j < NT; ++j) {
;     const bool more = j + 2 < NT;
;     if (more) DMA_K(j + 2, s2);
.LBB0_381:
	s_mov_b32 s10, s11
	s_setprio 2
	v_lshl_add_u32 v212, s10, 14, v201
	v_add_u32_e32 v144, v212, v225
	ds_read_b128 v[194:197], v144 offset:0
	ds_read_b128 v[214:217], v144 offset:0x2000
	v_xor_b32_e32 v144, 32, v225
	v_add_u32_e32 v144, v212, v144
	ds_read_b128 v[230:233], v144 offset:0
	ds_read_b128 v[234:237], v144 offset:0x2000
	v_xor_b32_e32 v144, 64, v225
	v_add_u32_e32 v144, v212, v144
	ds_read_b128 v[238:241], v144 offset:0
	ds_read_b128 v[242:245], v144 offset:0x2000
	v_xor_b32_e32 v144, 0x60, v225
	v_add_u32_e32 v144, v212, v144
	ds_read_b128 v[246:249], v144 offset:0
	ds_read_b128 v[220:223], v144 offset:0x2000
	s_add_i32 s11, s9, 2
	s_cmp_lt_u32 s11, s74
	s_cselect_b64 s[52:53], -1, 0
	s_cmp_ge_u32 s11, s74
	s_cselect_b64 s[50:51], -1, 0
	s_and_b64 vcc, exec, s[50:51]
	v_xor_b32_e32 v128, 0x80000000, v227
	v_mov_b32_e32 v129, v128
	v_mov_b32_e32 v130, v128
	v_mov_b32_e32 v131, v128
	v_mov_b32_e32 v132, v128
	v_mov_b32_e32 v133, v128
	v_mov_b32_e32 v134, v128
	v_mov_b32_e32 v135, v128
	v_mov_b32_e32 v136, v128
	v_mov_b32_e32 v137, v128
	v_mov_b32_e32 v138, v128
	v_mov_b32_e32 v139, v128
	v_mov_b32_e32 v140, v128
	v_mov_b32_e32 v141, v128
	v_mov_b32_e32 v142, v128
	v_mov_b32_e32 v143, v128
	s_waitcnt lgkmcnt(6)
	s_nop 1
	v_mfma_f32_32x32x16_bf16 v[144:159], v[194:197], v[188:191], v[128:143]
	v_mfma_f32_32x32x16_bf16 v[128:143], v[214:217], v[188:191], v[128:143]
	v_xor_b32_e32 v194, 0x80, v225
	v_add_u32_e32 v229, v212, v194
	ds_read_b128 v[194:197], v229 offset:0
	ds_read_b128 v[214:217], v229 offset:0x2000
	s_cbranch_vccnz .Lq1_nodma
	s_add_u32 s24, s60, 0xfffff100
	s_addc_u32 s25, s61, -1
	s_lshl_b32 s11, s7, 14
	s_add_i32 s11, s11, s0
	s_mov_b32 s12, m0
	s_mov_b32 m0, s11
	s_nop 0
	global_load_lds_dwordx4 v192, s[24:25]
	s_addk_i32 s11, 0x400
	s_mov_b32 m0, s11
	s_nop 0
	global_load_lds_dwordx4 v202, s[24:25]
	s_mov_b32 m0, s12
.Lq1_nodma:
	s_waitcnt lgkmcnt(6)
	v_mfma_f32_32x32x16_bf16 v[144:159], v[230:233], v[184:187], v[144:159]
	v_mfma_f32_32x32x16_bf16 v[128:143], v[234:237], v[184:187], v[128:143]
	v_xor_b32_e32 v229, 0xa0, v225
	v_add_u32_e32 v229, v212, v229
	ds_read_b128 v[230:233], v229 offset:0
	ds_read_b128 v[234:237], v229 offset:0x2000
	s_waitcnt lgkmcnt(6)
	v_mfma_f32_32x32x16_bf16 v[144:159], v[238:241], v[180:183], v[144:159]
	v_mfma_f32_32x32x16_bf16 v[128:143], v[242:245], v[180:183], v[128:143]
	v_xor_b32_e32 v229, 0xc0, v225
	v_add_u32_e32 v229, v212, v229
	ds_read_b128 v[238:241], v229 offset:0
	ds_read_b128 v[242:245], v229 offset:0x2000
	s_waitcnt lgkmcnt(6)
	v_mfma_f32_32x32x16_bf16 v[144:159], v[246:249], v[176:179], v[144:159]
	v_mfma_f32_32x32x16_bf16 v[128:143], v[220:223], v[176:179], v[128:143]
	v_xor_b32_e32 v220, 0xe0, v225
	v_add_u32_e32 v212, v212, v220
	ds_read_b128 v[220:223], v212 offset:0
	ds_read_b128 v[246:249], v212 offset:0x2000
	s_waitcnt lgkmcnt(6)
	v_mfma_f32_32x32x16_bf16 v[144:159], v[194:197], v[172:175], v[144:159]
	v_mfma_f32_32x32x16_bf16 v[128:143], v[214:217], v[172:175], v[128:143]
	s_waitcnt lgkmcnt(4)
	v_mfma_f32_32x32x16_bf16 v[144:159], v[230:233], v[168:171], v[144:159]
	v_mfma_f32_32x32x16_bf16 v[128:143], v[234:237], v[168:171], v[128:143]
	s_waitcnt lgkmcnt(2)
	v_mfma_f32_32x32x16_bf16 v[144:159], v[238:241], v[164:167], v[144:159]
	v_mfma_f32_32x32x16_bf16 v[128:143], v[242:245], v[164:167], v[128:143]
	s_waitcnt lgkmcnt(0)
	v_mfma_f32_32x32x16_bf16 v[144:159], v[220:223], v[160:163], v[144:159]
	s_cmp_eq_u32 s9, 0
	s_cselect_b64 s[56:57], -1, 0
	s_cmp_lg_u32 s9, 0
	v_mfma_f32_32x32x16_bf16 v[128:143], v[246:249], v[160:163], v[128:143]
	s_nop 7
	v_max_f32_e32 v194, v145, v145
	v_max_f32_e32 v195, v144, v144
	v_max_f32_e32 v194, v195, v194
	v_max3_f32 v194, v194, v146, v147
	v_max3_f32 v194, v194, v148, v149
	v_max3_f32 v195, v128, v129, v130
	v_max3_f32 v194, v194, v150, v151
	v_max3_f32 v195, v195, v131, v132
	v_max3_f32 v194, v194, v152, v153
	v_max3_f32 v195, v195, v133, v134
	v_max3_f32 v194, v194, v154, v155
	v_max3_f32 v195, v195, v135, v136
	v_max3_f32 v194, v194, v156, v157
	v_max3_f32 v195, v195, v137, v138
	v_max3_f32 v194, v194, v158, v159
	v_max3_f32 v195, v195, v139, v140
	v_max3_f32 v195, v195, v141, v142
	v_max3_f32 v194, v194, v195, v143
	v_mov_b32_e32 v195, v194
	s_nop 1
	v_permlane32_swap_b32_e32 v194, v195
	v_max_f32_e32 v195, v195, v195
	v_max_f32_e32 v194, v194, v194
	v_max_f32_e32 v229, v194, v195
	s_cbranch_scc0 .LBB0_404
	v_cmp_lt_f32_e32 vcc, s30, v229
	s_mov_b64 s[24:25], 0
	s_mov_b64 s[62:63], 0
	s_cbranch_vccnz .LBB0_405
	s_and_b64 vcc, exec, s[24:25]
	s_cbranch_vccnz .LBB0_406
